# SwiGLU epilogue runs at raised wave priority
# speedup vs baseline: 1.0104x; 1.0025x over previous
; __device__ __forceinline__ float siluf_(float x) { return x * __builtin_amdgcn_rcpf(1.f + __expf(-x)); }
;     ...
;           for (int mi = 0; mi < MI; mi++)
; #pragma unroll
;             for (int ni = 0; ni < 4; ni++)
;               acc[mi][ni] = __builtin_amdgcn_mfma_f32_16x16x32_bf16(bfr[ni], af[mi], acc[mi][ni], 0, 0, 0);
;     ...
;         } else if constexpr (EPI == EPI_SWIGLU) {
; #pragma unroll
;           for (int np = 0; np < 2; np++) {
;             const unsigned hc = ((unsigned)(n0 + wn * 64) >> 1) + np * 16 + fq * 4;
;             const f32x4 g = acc[mi][2 * np], u = acc[mi][2 * np + 1];
;             uint2 o;
;             o.x = pack2(siluf_(g[0]) * u[0], siluf_(g[1]) * u[1]);
;             o.y = pack2(siluf_(g[2]) * u[2], siluf_(g[3]) * u[3]);
;             *(uint2*)(e.b0 + (row * (unsigned)DFF + hc)) = o;
;           }
.Lsw_last:
	v_mfma_f32_16x16x32_bf16 v[134:137], v[194:197], v[156:159], v[134:137]
	v_mfma_f32_16x16x32_bf16 v[130:133], v[198:201], v[156:159], v[130:133]
	v_mfma_f32_16x16x32_bf16 v[126:129], v[202:205], v[156:159], v[126:129]
	v_mfma_f32_16x16x32_bf16 v[122:125], v[226:229], v[156:159], v[122:125]
	v_mfma_f32_16x16x32_bf16 v[118:121], v[194:197], v[166:169], v[118:121]
	v_mfma_f32_16x16x32_bf16 v[114:117], v[198:201], v[166:169], v[114:117]
	v_mfma_f32_16x16x32_bf16 v[110:113], v[202:205], v[166:169], v[110:113]
	v_mfma_f32_16x16x32_bf16 v[106:109], v[226:229], v[166:169], v[106:109]
	v_mfma_f32_16x16x32_bf16 v[102:105], v[194:197], v[170:173], v[102:105]
	v_mfma_f32_16x16x32_bf16 v[98:101], v[198:201], v[170:173], v[98:101]
	v_mfma_f32_16x16x32_bf16 v[94:97], v[202:205], v[170:173], v[94:97]
	v_mfma_f32_16x16x32_bf16 v[90:93], v[226:229], v[170:173], v[90:93]
	v_mfma_f32_16x16x32_bf16 v[86:89], v[194:197], v[174:177], v[86:89]
	v_mfma_f32_16x16x32_bf16 v[82:85], v[198:201], v[174:177], v[82:85]
	v_mfma_f32_16x16x32_bf16 v[78:81], v[202:205], v[174:177], v[78:81]
	v_mfma_f32_16x16x32_bf16 v[74:77], v[226:229], v[174:177], v[74:77]
	v_mfma_f32_16x16x32_bf16 v[70:73], v[194:197], v[178:181], v[70:73]
	v_mfma_f32_16x16x32_bf16 v[66:69], v[198:201], v[178:181], v[66:69]
	v_mfma_f32_16x16x32_bf16 v[62:65], v[202:205], v[178:181], v[62:65]
	v_mfma_f32_16x16x32_bf16 v[58:61], v[226:229], v[178:181], v[58:61]
	v_mfma_f32_16x16x32_bf16 v[54:57], v[194:197], v[182:185], v[54:57]
	v_mfma_f32_16x16x32_bf16 v[50:53], v[198:201], v[182:185], v[50:53]
	v_mfma_f32_16x16x32_bf16 v[46:49], v[202:205], v[182:185], v[46:49]
	v_mfma_f32_16x16x32_bf16 v[42:45], v[226:229], v[182:185], v[42:45]
	v_mfma_f32_16x16x32_bf16 v[38:41], v[194:197], v[186:189], v[38:41]
	v_mfma_f32_16x16x32_bf16 v[34:37], v[198:201], v[186:189], v[34:37]
	v_mfma_f32_16x16x32_bf16 v[30:33], v[202:205], v[186:189], v[30:33]
	v_mfma_f32_16x16x32_bf16 v[26:29], v[226:229], v[186:189], v[26:29]
	v_mfma_f32_16x16x32_bf16 v[22:25], v[194:197], v[190:193], v[22:25]
	v_mfma_f32_16x16x32_bf16 v[18:21], v[198:201], v[190:193], v[18:21]
	v_mfma_f32_16x16x32_bf16 v[14:17], v[202:205], v[190:193], v[14:17]
	v_mfma_f32_16x16x32_bf16 v[10:13], v[226:229], v[190:193], v[10:13]
	s_setprio 2
	v_or_b32_e32 v8, s8, v148
	v_lshrrev_b32_e32 v8, 1, v8
	v_add_u32_e32 v142, s7, v150
	v_or_b32_e32 v8, v8, v149
	s_movk_i32 s4, 0xb00
	v_mad_u64_u32 v[142:143], s[4:5], v142, s4, v[8:9]
	v_bfe_u32 v144, v2, 4, 1
	v_mul_u32_u24_e32 v144, 12, v144
	s_nop 0
	v_add_u32_e32 v142, v142, v144
	v_mul_f32_e32 v174, 0xbfb8aa3b, v134
	v_mul_f32_e32 v175, 0xbfb8aa3b, v135
	v_mul_f32_e32 v176, 0xbfb8aa3b, v136
	v_mul_f32_e32 v177, 0xbfb8aa3b, v137
	v_mul_f32_e32 v178, 0xbfb8aa3b, v126
	v_mul_f32_e32 v179, 0xbfb8aa3b, v127
	v_mul_f32_e32 v180, 0xbfb8aa3b, v128
	v_mul_f32_e32 v181, 0xbfb8aa3b, v129
	v_exp_f32_e32 v174, v174
	v_exp_f32_e32 v175, v175
	v_exp_f32_e32 v176, v176
	v_exp_f32_e32 v177, v177
	v_exp_f32_e32 v178, v178
	v_exp_f32_e32 v179, v179
	v_exp_f32_e32 v180, v180
	v_exp_f32_e32 v181, v181
	v_add_f32_e32 v174, 1.0, v174
	v_add_f32_e32 v175, 1.0, v175
	v_add_f32_e32 v176, 1.0, v176
	v_add_f32_e32 v177, 1.0, v177
	v_add_f32_e32 v178, 1.0, v178
	v_add_f32_e32 v179, 1.0, v179
	v_add_f32_e32 v180, 1.0, v180
	v_add_f32_e32 v181, 1.0, v181
	v_rcp_f32_e32 v174, v174
	v_rcp_f32_e32 v175, v175
	v_rcp_f32_e32 v176, v176
	v_rcp_f32_e32 v177, v177
	v_rcp_f32_e32 v178, v178
	v_rcp_f32_e32 v179, v179
	v_rcp_f32_e32 v180, v180
	v_rcp_f32_e32 v181, v181
	v_mov_b32_e32 v8, v142
	v_pk_mul_f32 v[134:135], v[134:135], v[174:175]
	v_pk_mul_f32 v[136:137], v[136:137], v[176:177]
	v_pk_mul_f32 v[126:127], v[126:127], v[178:179]
	v_pk_mul_f32 v[128:129], v[128:129], v[180:181]
	v_lshl_add_u64 v[182:183], v[8:9], 1, s[52:53]
	v_pk_mul_f32 v[130:131], v[130:131], v[134:135]
	v_pk_mul_f32 v[132:133], v[132:133], v[136:137]
	v_pk_mul_f32 v[122:123], v[122:123], v[126:127]
	v_pk_mul_f32 v[124:125], v[124:125], v[128:129]
	v_cvt_pk_bf16_f32 v166, v130, v131
	v_cvt_pk_bf16_f32 v167, v132, v133
	v_cvt_pk_bf16_f32 v168, v122, v123
	v_cvt_pk_bf16_f32 v169, v124, v125
	s_nop 1
	v_permlane16_swap_b32 v166, v168
	v_permlane16_swap_b32 v167, v169
	s_nop 1
	global_store_dwordx4 v[182:183], v[166:169], off
	v_mul_f32_e32 v174, 0xbfb8aa3b, v118
	v_mul_f32_e32 v175, 0xbfb8aa3b, v119
	v_mul_f32_e32 v176, 0xbfb8aa3b, v120
	v_mul_f32_e32 v177, 0xbfb8aa3b, v121
	v_mul_f32_e32 v178, 0xbfb8aa3b, v110
	v_mul_f32_e32 v179, 0xbfb8aa3b, v111
	v_mul_f32_e32 v180, 0xbfb8aa3b, v112
	v_mul_f32_e32 v181, 0xbfb8aa3b, v113
	v_exp_f32_e32 v174, v174
	v_exp_f32_e32 v175, v175
	v_exp_f32_e32 v176, v176
	v_exp_f32_e32 v177, v177
	v_exp_f32_e32 v178, v178
	v_exp_f32_e32 v179, v179
	v_exp_f32_e32 v180, v180
	v_exp_f32_e32 v181, v181
	v_add_f32_e32 v174, 1.0, v174
	v_add_f32_e32 v175, 1.0, v175
	v_add_f32_e32 v176, 1.0, v176
	v_add_f32_e32 v177, 1.0, v177
	v_add_f32_e32 v178, 1.0, v178
	v_add_f32_e32 v179, 1.0, v179
	v_add_f32_e32 v180, 1.0, v180
	v_add_f32_e32 v181, 1.0, v181
	v_rcp_f32_e32 v174, v174
	v_rcp_f32_e32 v175, v175
	v_rcp_f32_e32 v176, v176
	v_rcp_f32_e32 v177, v177
	v_rcp_f32_e32 v178, v178
	v_rcp_f32_e32 v179, v179
	v_rcp_f32_e32 v180, v180
	v_rcp_f32_e32 v181, v181
	v_add_u32_e32 v8, 0xb000, v142
	v_pk_mul_f32 v[118:119], v[118:119], v[174:175]
	v_pk_mul_f32 v[120:121], v[120:121], v[176:177]
	v_pk_mul_f32 v[110:111], v[110:111], v[178:179]
	v_pk_mul_f32 v[112:113], v[112:113], v[180:181]
	v_lshl_add_u64 v[184:185], v[8:9], 1, s[52:53]
	v_pk_mul_f32 v[114:115], v[114:115], v[118:119]
	v_pk_mul_f32 v[116:117], v[116:117], v[120:121]
	v_pk_mul_f32 v[106:107], v[106:107], v[110:111]
; __device__ __forceinline__ float siluf_(float x) { return x * __builtin_amdgcn_rcpf(1.f + __expf(-x)); }
;     ...
;         } else if constexpr (EPI == EPI_SWIGLU) {
; #pragma unroll
;           for (int np = 0; np < 2; np++) {
;             const unsigned hc = ((unsigned)(n0 + wn * 64) >> 1) + np * 16 + fq * 4;
;             const f32x4 g = acc[mi][2 * np], u = acc[mi][2 * np + 1];
;             uint2 o;
;             o.x = pack2(siluf_(g[0]) * u[0], siluf_(g[1]) * u[1]);
;             o.y = pack2(siluf_(g[2]) * u[2], siluf_(g[3]) * u[3]);
;             *(uint2*)(e.b0 + (row * (unsigned)DFF + hc)) = o;
;           }
	v_pk_mul_f32 v[108:109], v[108:109], v[112:113]
	v_cvt_pk_bf16_f32 v170, v114, v115
	v_cvt_pk_bf16_f32 v171, v116, v117
	v_cvt_pk_bf16_f32 v172, v106, v107
	v_cvt_pk_bf16_f32 v173, v108, v109
	s_nop 1
	v_permlane16_swap_b32 v170, v172
	v_permlane16_swap_b32 v171, v173
	s_nop 1
	global_store_dwordx4 v[184:185], v[170:173], off
	v_mul_f32_e32 v174, 0xbfb8aa3b, v102
	v_mul_f32_e32 v175, 0xbfb8aa3b, v103
	v_mul_f32_e32 v176, 0xbfb8aa3b, v104
	v_mul_f32_e32 v177, 0xbfb8aa3b, v105
	v_mul_f32_e32 v178, 0xbfb8aa3b, v94
	v_mul_f32_e32 v179, 0xbfb8aa3b, v95
	v_mul_f32_e32 v180, 0xbfb8aa3b, v96
	v_mul_f32_e32 v181, 0xbfb8aa3b, v97
	v_exp_f32_e32 v174, v174
	v_exp_f32_e32 v175, v175
	v_exp_f32_e32 v176, v176
	v_exp_f32_e32 v177, v177
	v_exp_f32_e32 v178, v178
	v_exp_f32_e32 v179, v179
	v_exp_f32_e32 v180, v180
	v_exp_f32_e32 v181, v181
	v_add_f32_e32 v174, 1.0, v174
	v_add_f32_e32 v175, 1.0, v175
	v_add_f32_e32 v176, 1.0, v176
	v_add_f32_e32 v177, 1.0, v177
	v_add_f32_e32 v178, 1.0, v178
	v_add_f32_e32 v179, 1.0, v179
	v_add_f32_e32 v180, 1.0, v180
	v_add_f32_e32 v181, 1.0, v181
	v_rcp_f32_e32 v174, v174
	v_rcp_f32_e32 v175, v175
	v_rcp_f32_e32 v176, v176
	v_rcp_f32_e32 v177, v177
	v_rcp_f32_e32 v178, v178
	v_rcp_f32_e32 v179, v179
	v_rcp_f32_e32 v180, v180
	v_rcp_f32_e32 v181, v181
	v_add_u32_e32 v8, 0x16000, v142
	v_pk_mul_f32 v[102:103], v[102:103], v[174:175]
	v_pk_mul_f32 v[104:105], v[104:105], v[176:177]
	v_pk_mul_f32 v[94:95], v[94:95], v[178:179]
	v_pk_mul_f32 v[96:97], v[96:97], v[180:181]
	v_lshl_add_u64 v[182:183], v[8:9], 1, s[52:53]
	v_pk_mul_f32 v[98:99], v[98:99], v[102:103]
	v_pk_mul_f32 v[100:101], v[100:101], v[104:105]
	v_pk_mul_f32 v[90:91], v[90:91], v[94:95]
	v_pk_mul_f32 v[92:93], v[92:93], v[96:97]
	v_cvt_pk_bf16_f32 v166, v98, v99
	v_cvt_pk_bf16_f32 v167, v100, v101
	v_cvt_pk_bf16_f32 v168, v90, v91
	v_cvt_pk_bf16_f32 v169, v92, v93
	s_nop 1
	v_permlane16_swap_b32 v166, v168
	v_permlane16_swap_b32 v167, v169
	s_nop 1
	global_store_dwordx4 v[182:183], v[166:169], off
	v_mul_f32_e32 v174, 0xbfb8aa3b, v86
	v_mul_f32_e32 v175, 0xbfb8aa3b, v87
	v_mul_f32_e32 v176, 0xbfb8aa3b, v88
	v_mul_f32_e32 v177, 0xbfb8aa3b, v89
	v_mul_f32_e32 v178, 0xbfb8aa3b, v78
	v_mul_f32_e32 v179, 0xbfb8aa3b, v79
	v_mul_f32_e32 v180, 0xbfb8aa3b, v80
	v_mul_f32_e32 v181, 0xbfb8aa3b, v81
	v_exp_f32_e32 v174, v174
	v_exp_f32_e32 v175, v175
	v_exp_f32_e32 v176, v176
	v_exp_f32_e32 v177, v177
	v_exp_f32_e32 v178, v178
	v_exp_f32_e32 v179, v179
	v_exp_f32_e32 v180, v180
	v_exp_f32_e32 v181, v181
	v_add_f32_e32 v174, 1.0, v174
	v_add_f32_e32 v175, 1.0, v175
	v_add_f32_e32 v176, 1.0, v176
	v_add_f32_e32 v177, 1.0, v177
	v_add_f32_e32 v178, 1.0, v178
	v_add_f32_e32 v179, 1.0, v179
	v_add_f32_e32 v180, 1.0, v180
	v_add_f32_e32 v181, 1.0, v181
	v_rcp_f32_e32 v174, v174
	v_rcp_f32_e32 v175, v175
	v_rcp_f32_e32 v176, v176
	v_rcp_f32_e32 v177, v177
	v_rcp_f32_e32 v178, v178
	v_rcp_f32_e32 v179, v179
	v_rcp_f32_e32 v180, v180
	v_rcp_f32_e32 v181, v181
	v_add_u32_e32 v8, 0x21000, v142
	v_pk_mul_f32 v[86:87], v[86:87], v[174:175]
	v_pk_mul_f32 v[88:89], v[88:89], v[176:177]
	v_pk_mul_f32 v[78:79], v[78:79], v[178:179]
	v_pk_mul_f32 v[80:81], v[80:81], v[180:181]
	v_lshl_add_u64 v[184:185], v[8:9], 1, s[52:53]
	v_pk_mul_f32 v[82:83], v[82:83], v[86:87]
	v_pk_mul_f32 v[84:85], v[84:85], v[88:89]
	v_pk_mul_f32 v[74:75], v[74:75], v[78:79]
	v_pk_mul_f32 v[76:77], v[76:77], v[80:81]
	v_cvt_pk_bf16_f32 v170, v82, v83
	v_cvt_pk_bf16_f32 v171, v84, v85
	v_cvt_pk_bf16_f32 v172, v74, v75
	v_cvt_pk_bf16_f32 v173, v76, v77
	s_nop 1
	v_permlane16_swap_b32 v170, v172
	v_permlane16_swap_b32 v171, v173
	s_nop 1
	global_store_dwordx4 v[184:185], v[170:173], off
	v_mul_f32_e32 v174, 0xbfb8aa3b, v70
	v_mul_f32_e32 v175, 0xbfb8aa3b, v71
	v_mul_f32_e32 v176, 0xbfb8aa3b, v72
	v_mul_f32_e32 v177, 0xbfb8aa3b, v73
	v_mul_f32_e32 v178, 0xbfb8aa3b, v62
	v_mul_f32_e32 v179, 0xbfb8aa3b, v63
	v_mul_f32_e32 v180, 0xbfb8aa3b, v64
	v_mul_f32_e32 v181, 0xbfb8aa3b, v65
	v_exp_f32_e32 v174, v174
	v_exp_f32_e32 v175, v175
	v_exp_f32_e32 v176, v176
	v_exp_f32_e32 v177, v177
	v_exp_f32_e32 v178, v178
	v_exp_f32_e32 v179, v179
	v_exp_f32_e32 v180, v180
	v_exp_f32_e32 v181, v181
	v_add_f32_e32 v174, 1.0, v174
	v_add_f32_e32 v175, 1.0, v175
	v_add_f32_e32 v176, 1.0, v176
	v_add_f32_e32 v177, 1.0, v177
	v_add_f32_e32 v178, 1.0, v178
	v_add_f32_e32 v179, 1.0, v179
	v_add_f32_e32 v180, 1.0, v180
	v_add_f32_e32 v181, 1.0, v181
	v_rcp_f32_e32 v174, v174
	v_rcp_f32_e32 v175, v175
	v_rcp_f32_e32 v176, v176
	v_rcp_f32_e32 v177, v177
	v_rcp_f32_e32 v178, v178
	v_rcp_f32_e32 v179, v179
	v_rcp_f32_e32 v180, v180
	v_rcp_f32_e32 v181, v181
	v_add_u32_e32 v8, 0x2c000, v142
	v_pk_mul_f32 v[70:71], v[70:71], v[174:175]
	v_pk_mul_f32 v[72:73], v[72:73], v[176:177]
	v_pk_mul_f32 v[62:63], v[62:63], v[178:179]
	v_pk_mul_f32 v[64:65], v[64:65], v[180:181]
	v_lshl_add_u64 v[182:183], v[8:9], 1, s[52:53]
	v_pk_mul_f32 v[66:67], v[66:67], v[70:71]
	v_pk_mul_f32 v[68:69], v[68:69], v[72:73]
	v_pk_mul_f32 v[58:59], v[58:59], v[62:63]
	v_pk_mul_f32 v[60:61], v[60:61], v[64:65]
	v_cvt_pk_bf16_f32 v166, v66, v67
	v_cvt_pk_bf16_f32 v167, v68, v69
	v_cvt_pk_bf16_f32 v168, v58, v59
	v_cvt_pk_bf16_f32 v169, v60, v61
; __device__ __forceinline__ float siluf_(float x) { return x * __builtin_amdgcn_rcpf(1.f + __expf(-x)); }
;     ...
;   for (int it = 0;; it++) {
;     int tile;
;     if (nb == 512) tile = ((it * 8 + (bid & 7)) << 6) + (bid >> 3); else tile = it * nb + bid;
;     tile += tbeg;
;     if (tile >= MTX * ntn || tile >= tend) break;
;     ...
;         } else if constexpr (EPI == EPI_SWIGLU) {
; #pragma unroll
;           for (int np = 0; np < 2; np++) {
;             const unsigned hc = ((unsigned)(n0 + wn * 64) >> 1) + np * 16 + fq * 4;
;             const f32x4 g = acc[mi][2 * np], u = acc[mi][2 * np + 1];
;             uint2 o;
;             o.x = pack2(siluf_(g[0]) * u[0], siluf_(g[1]) * u[1]);
;             o.y = pack2(siluf_(g[2]) * u[2], siluf_(g[3]) * u[3]);
;             *(uint2*)(e.b0 + (row * (unsigned)DFF + hc)) = o;
;           }
	s_nop 1
	v_permlane16_swap_b32 v166, v168
	v_permlane16_swap_b32 v167, v169
	s_nop 1
	global_store_dwordx4 v[182:183], v[166:169], off
	v_mul_f32_e32 v174, 0xbfb8aa3b, v54
	v_mul_f32_e32 v175, 0xbfb8aa3b, v55
	v_mul_f32_e32 v176, 0xbfb8aa3b, v56
	v_mul_f32_e32 v177, 0xbfb8aa3b, v57
	v_mul_f32_e32 v178, 0xbfb8aa3b, v46
	v_mul_f32_e32 v179, 0xbfb8aa3b, v47
	v_mul_f32_e32 v180, 0xbfb8aa3b, v48
	v_mul_f32_e32 v181, 0xbfb8aa3b, v49
	v_exp_f32_e32 v174, v174
	v_exp_f32_e32 v175, v175
	v_exp_f32_e32 v176, v176
	v_exp_f32_e32 v177, v177
	v_exp_f32_e32 v178, v178
	v_exp_f32_e32 v179, v179
	v_exp_f32_e32 v180, v180
	v_exp_f32_e32 v181, v181
	v_add_f32_e32 v174, 1.0, v174
	v_add_f32_e32 v175, 1.0, v175
	v_add_f32_e32 v176, 1.0, v176
	v_add_f32_e32 v177, 1.0, v177
	v_add_f32_e32 v178, 1.0, v178
	v_add_f32_e32 v179, 1.0, v179
	v_add_f32_e32 v180, 1.0, v180
	v_add_f32_e32 v181, 1.0, v181
	v_rcp_f32_e32 v174, v174
	v_rcp_f32_e32 v175, v175
	v_rcp_f32_e32 v176, v176
	v_rcp_f32_e32 v177, v177
	v_rcp_f32_e32 v178, v178
	v_rcp_f32_e32 v179, v179
	v_rcp_f32_e32 v180, v180
	v_rcp_f32_e32 v181, v181
	v_add_u32_e32 v8, 0x37000, v142
	v_pk_mul_f32 v[54:55], v[54:55], v[174:175]
	v_pk_mul_f32 v[56:57], v[56:57], v[176:177]
	v_pk_mul_f32 v[46:47], v[46:47], v[178:179]
	v_pk_mul_f32 v[48:49], v[48:49], v[180:181]
	v_lshl_add_u64 v[184:185], v[8:9], 1, s[52:53]
	v_pk_mul_f32 v[50:51], v[50:51], v[54:55]
	v_pk_mul_f32 v[52:53], v[52:53], v[56:57]
	v_pk_mul_f32 v[42:43], v[42:43], v[46:47]
	v_pk_mul_f32 v[44:45], v[44:45], v[48:49]
	v_cvt_pk_bf16_f32 v170, v50, v51
	v_cvt_pk_bf16_f32 v171, v52, v53
	v_cvt_pk_bf16_f32 v172, v42, v43
	v_cvt_pk_bf16_f32 v173, v44, v45
	s_nop 1
	v_permlane16_swap_b32 v170, v172
	v_permlane16_swap_b32 v171, v173
	s_nop 1
	global_store_dwordx4 v[184:185], v[170:173], off
	v_mul_f32_e32 v174, 0xbfb8aa3b, v38
	v_mul_f32_e32 v175, 0xbfb8aa3b, v39
	v_mul_f32_e32 v176, 0xbfb8aa3b, v40
	v_mul_f32_e32 v177, 0xbfb8aa3b, v41
	v_mul_f32_e32 v178, 0xbfb8aa3b, v30
	v_mul_f32_e32 v179, 0xbfb8aa3b, v31
	v_mul_f32_e32 v180, 0xbfb8aa3b, v32
	v_mul_f32_e32 v181, 0xbfb8aa3b, v33
	v_exp_f32_e32 v174, v174
	v_exp_f32_e32 v175, v175
	v_exp_f32_e32 v176, v176
	v_exp_f32_e32 v177, v177
	v_exp_f32_e32 v178, v178
	v_exp_f32_e32 v179, v179
	v_exp_f32_e32 v180, v180
	v_exp_f32_e32 v181, v181
	v_add_f32_e32 v174, 1.0, v174
	v_add_f32_e32 v175, 1.0, v175
	v_add_f32_e32 v176, 1.0, v176
	v_add_f32_e32 v177, 1.0, v177
	v_add_f32_e32 v178, 1.0, v178
	v_add_f32_e32 v179, 1.0, v179
	v_add_f32_e32 v180, 1.0, v180
	v_add_f32_e32 v181, 1.0, v181
	v_rcp_f32_e32 v174, v174
	v_rcp_f32_e32 v175, v175
	v_rcp_f32_e32 v176, v176
	v_rcp_f32_e32 v177, v177
	v_rcp_f32_e32 v178, v178
	v_rcp_f32_e32 v179, v179
	v_rcp_f32_e32 v180, v180
	v_rcp_f32_e32 v181, v181
	v_add_u32_e32 v8, 0x42000, v142
	v_pk_mul_f32 v[38:39], v[38:39], v[174:175]
	v_pk_mul_f32 v[40:41], v[40:41], v[176:177]
	v_pk_mul_f32 v[30:31], v[30:31], v[178:179]
	v_pk_mul_f32 v[32:33], v[32:33], v[180:181]
	v_lshl_add_u64 v[182:183], v[8:9], 1, s[52:53]
	v_pk_mul_f32 v[34:35], v[34:35], v[38:39]
	v_pk_mul_f32 v[36:37], v[36:37], v[40:41]
	v_pk_mul_f32 v[26:27], v[26:27], v[30:31]
	v_pk_mul_f32 v[28:29], v[28:29], v[32:33]
	v_cvt_pk_bf16_f32 v166, v34, v35
	v_cvt_pk_bf16_f32 v167, v36, v37
	v_cvt_pk_bf16_f32 v168, v26, v27
	v_cvt_pk_bf16_f32 v169, v28, v29
	s_nop 1
	v_permlane16_swap_b32 v166, v168
	v_permlane16_swap_b32 v167, v169
	s_nop 1
	global_store_dwordx4 v[182:183], v[166:169], off
	v_mul_f32_e32 v174, 0xbfb8aa3b, v22
	v_mul_f32_e32 v175, 0xbfb8aa3b, v23
	v_mul_f32_e32 v176, 0xbfb8aa3b, v24
	v_mul_f32_e32 v177, 0xbfb8aa3b, v25
	v_mul_f32_e32 v178, 0xbfb8aa3b, v14
	v_mul_f32_e32 v179, 0xbfb8aa3b, v15
	v_mul_f32_e32 v180, 0xbfb8aa3b, v16
	v_mul_f32_e32 v181, 0xbfb8aa3b, v17
	v_exp_f32_e32 v174, v174
	v_exp_f32_e32 v175, v175
	v_exp_f32_e32 v176, v176
	v_exp_f32_e32 v177, v177
	v_exp_f32_e32 v178, v178
	v_exp_f32_e32 v179, v179
	v_exp_f32_e32 v180, v180
	v_exp_f32_e32 v181, v181
	v_add_f32_e32 v174, 1.0, v174
	v_add_f32_e32 v175, 1.0, v175
	v_add_f32_e32 v176, 1.0, v176
	v_add_f32_e32 v177, 1.0, v177
	v_add_f32_e32 v178, 1.0, v178
	v_add_f32_e32 v179, 1.0, v179
	v_add_f32_e32 v180, 1.0, v180
	v_add_f32_e32 v181, 1.0, v181
	v_rcp_f32_e32 v174, v174
	v_rcp_f32_e32 v175, v175
	v_rcp_f32_e32 v176, v176
	v_rcp_f32_e32 v177, v177
	v_rcp_f32_e32 v178, v178
	v_rcp_f32_e32 v179, v179
	v_rcp_f32_e32 v180, v180
	v_rcp_f32_e32 v181, v181
	v_add_u32_e32 v8, 0x4d000, v142
	v_pk_mul_f32 v[22:23], v[22:23], v[174:175]
	v_pk_mul_f32 v[24:25], v[24:25], v[176:177]
	v_pk_mul_f32 v[14:15], v[14:15], v[178:179]
	v_pk_mul_f32 v[16:17], v[16:17], v[180:181]
	v_lshl_add_u64 v[184:185], v[8:9], 1, s[52:53]
	v_pk_mul_f32 v[18:19], v[18:19], v[22:23]
	v_pk_mul_f32 v[20:21], v[20:21], v[24:25]
	v_pk_mul_f32 v[10:11], v[10:11], v[14:15]
	v_pk_mul_f32 v[12:13], v[12:13], v[16:17]
	v_cvt_pk_bf16_f32 v170, v18, v19
	v_cvt_pk_bf16_f32 v171, v20, v21
	v_cvt_pk_bf16_f32 v172, v10, v11
	v_cvt_pk_bf16_f32 v173, v12, v13
	s_nop 1
	v_permlane16_swap_b32 v170, v172
	v_permlane16_swap_b32 v171, v173
	s_nop 1
	global_store_dwordx4 v[184:185], v[170:173], off
	s_setprio 0
	s_add_i32 s6, s6, 1
	s_mov_b64 s[4:5], 0
	s_branch .LBB0_2615
